# gemm1/gemm2 K-loops: LDS-DMA source addresses from SGPR base + 32-bit lane offset (no 64-bit VALU adds in the loading wave beside the partner's MFMA block); rest as v74
# speedup vs baseline: 1.0063x; 1.0012x over previous
; #define PG8_STAGE(bufoff, gbase, voff) do { _Pragma("unroll") for (int _i = 0; _i < 2; ++_i) \
;         __builtin_amdgcn_global_load_lds((const unsigned*)((const char*)(gbase) + (voff)[_i]), (PG8_LAS unsigned*)(lds + (bufoff) + ldsw + _i * 8192), 16, 0, 0); } while (0)
; #define PG8_LDA(dst, b, h) do { _Pragma("unroll") for (int m = 0; m < 4; ++m) _Pragma("unroll") for (int k = 0; k < 2; ++k) dst[m][k] = *(const PG8_LAS bf16x8*)(lds + PG8_SA(b, h) + aoff + m * 2048 + k * 1024); } while (0)
; #define PG8_LDB(dst, b, h) do { _Pragma("unroll") for (int n = 0; n < 2; ++n) _Pragma("unroll") for (int k = 0; k < 2; ++k) dst[n][k] = *(const PG8_LAS bf16x8*)(lds + PG8_SB(b, h) + boff + n * 2048 + k * 1024); } while (0)
; #define PG8_MMA(ai, bj, At, Bt) do { __builtin_amdgcn_s_setprio(1); _Pragma("unroll") for (int m = 0; m < 4; ++m) _Pragma("unroll") for (int n = 0; n < 2; ++n) _Pragma("unroll") for (int k = 0; k < 2; ++k) \
;         acc[ai][bj][m][n] = __builtin_amdgcn_mfma_f32_16x16x32_bf16(Bt[n][k], At[m][k], acc[ai][bj][m][n], 0, 0, 0); __builtin_amdgcn_s_setprio(0); } while (0)
; #define PG8_WAIT_V(n) asm volatile("s_waitcnt vmcnt(" #n ")" ::: "memory")
; #define PG8_BAR __builtin_amdgcn_s_barrier()
; template <class Epi, class Sched, bool ALIGN_EPI = false, bool SP2 = false>
; __device__ __forceinline__ void gemm_phase(PG8_LAS unsigned char* lds, const Gemm g, const Sched& S, const Epi& E) {
;     ...
;         for (int t = 0; t < nt; t += 2) {
;             const bool last = (t == nt - 2);
;             const char* a1 = cA + (size_t)(t + 1) * kstep;
;             const char* a2 = last ? nA : cA + (size_t)(t + 2) * kstep; const char* b2 = last ? nB : cB + (size_t)(t + 2) * kstep;
;             const char* a3 = a2 + kstep; const char* b3 = b2 + kstep;
;             if (last && has_next) S.a_ready(nxt);
;             if constexpr (SP2) {
;             PG8_LDB(B0, 0, 0); PG8_LDB(B1, 0, 1); PG8_SCHED; PG8_LDA(At, 0, 0); PG8_STAGE(PG8_SA(1, 1), a1 + hstep, voffA);
;             PG8_WAIT_V(8); PG8_WAIT_L(0); PG8_BAR; PG8_MMA(0, 0, At, B0); PG8_MMA(0, 1, At, B1); PG8_BAR; PG8_SCHED;
;             PG8_LDA(At, 0, 1); PG8_STAGE(PG8_SB(0, 0), b2, voffB); PG8_STAGE(PG8_SB(0, 1), b2 + hstep, voffB); PG8_STAGE(PG8_SA(0, 0), a2, voffA);
;             PG8_WAIT_V(8); PG8_WAIT_L(0); PG8_BAR; PG8_MMA(1, 0, At, B0); PG8_MMA(1, 1, At, B1); PG8_BAR; PG8_SCHED;
.LBB0_230:
	s_add_u32 s35, s62, 0xfffc0080
	s_addc_u32 s64, s63, -1
	s_add_i32 s68, 0, 0x10000
	s_cmp_eq_u32 s33, 12
	s_cselect_b32 s67, s1, s64
	s_cselect_b32 s66, s14, s35
	v_add_u32_e32 v0, s68, v185
	s_cselect_b32 s65, s15, s29
	s_cselect_b32 s64, s20, s28
	s_add_i32 s35, 0, 0x14000
	ds_read_b128 v[130:133], v0
	ds_read_b128 v[134:137], v0 offset:1024
	ds_read_b128 v[138:141], v0 offset:2048
	ds_read_b128 v[142:145], v0 offset:3072
	v_add_u32_e32 v0, s35, v185
	ds_read_b128 v[146:149], v0
	ds_read_b128 v[150:153], v0 offset:1024
	ds_read_b128 v[154:157], v0 offset:2048
	ds_read_b128 v[158:161], v0 offset:3072
	s_add_i32 m0, s82, 0xc000
	ds_read_b128 v[162:165], v187
	ds_read_b128 v[166:169], v187 offset:1024
	ds_read_b128 v[170:173], v187 offset:2048
	ds_read_b128 v[174:177], v187 offset:3072
	ds_read_b128 v[210:213], v187 offset:4096
	ds_read_b128 v[214:217], v187 offset:5120
	ds_read_b128 v[228:231], v187 offset:6144
	ds_read_b128 v[232:235], v187 offset:7168
	global_load_lds_dwordx4 v208, s[62:63]
	s_add_i32 m0, s82, 0xe000
	s_nop 0
	global_load_lds_dwordx4 v206, s[62:63]
	s_waitcnt vmcnt(8)
	s_waitcnt lgkmcnt(0)
	s_barrier
	s_setprio 1
	s_waitcnt lgkmcnt(0)
	v_mfma_f32_16x16x32_bf16 v[126:129], v[130:133], v[162:165], v[126:129]
	v_mfma_f32_16x16x32_bf16 v[122:125], v[138:141], v[162:165], v[122:125]
	v_mfma_f32_16x16x32_bf16 v[94:97], v[130:133], v[170:173], v[94:97]
	v_mfma_f32_16x16x32_bf16 v[90:93], v[138:141], v[170:173], v[90:93]
	v_mfma_f32_16x16x32_bf16 v[62:65], v[130:133], v[210:213], v[62:65]
	v_mfma_f32_16x16x32_bf16 v[58:61], v[138:141], v[210:213], v[58:61]
	v_mfma_f32_16x16x32_bf16 v[30:33], v[130:133], v[228:231], v[30:33]
	v_mfma_f32_16x16x32_bf16 v[26:29], v[138:141], v[228:231], v[26:29]
	v_mfma_f32_16x16x32_bf16 v[126:129], v[134:137], v[166:169], v[126:129]
	v_mfma_f32_16x16x32_bf16 v[122:125], v[142:145], v[166:169], v[122:125]
	v_mfma_f32_16x16x32_bf16 v[94:97], v[134:137], v[174:177], v[94:97]
	v_mfma_f32_16x16x32_bf16 v[90:93], v[142:145], v[174:177], v[90:93]
	v_mfma_f32_16x16x32_bf16 v[62:65], v[134:137], v[214:217], v[62:65]
	v_mfma_f32_16x16x32_bf16 v[58:61], v[142:145], v[214:217], v[58:61]
	v_mfma_f32_16x16x32_bf16 v[30:33], v[134:137], v[232:235], v[30:33]
	v_mfma_f32_16x16x32_bf16 v[26:29], v[142:145], v[232:235], v[26:29]
	s_setprio 0
	s_setprio 1
	v_mfma_f32_16x16x32_bf16 v[118:121], v[146:149], v[162:165], v[118:121]
	v_mfma_f32_16x16x32_bf16 v[114:117], v[154:157], v[162:165], v[114:117]
	v_mfma_f32_16x16x32_bf16 v[86:89], v[146:149], v[170:173], v[86:89]
	v_mfma_f32_16x16x32_bf16 v[82:85], v[154:157], v[170:173], v[82:85]
	v_mfma_f32_16x16x32_bf16 v[54:57], v[146:149], v[210:213], v[54:57]
	v_mfma_f32_16x16x32_bf16 v[50:53], v[154:157], v[210:213], v[50:53]
	v_mfma_f32_16x16x32_bf16 v[22:25], v[146:149], v[228:231], v[22:25]
	v_mfma_f32_16x16x32_bf16 v[18:21], v[154:157], v[228:231], v[18:21]
	v_mfma_f32_16x16x32_bf16 v[118:121], v[150:153], v[166:169], v[118:121]
	v_mfma_f32_16x16x32_bf16 v[114:117], v[158:161], v[166:169], v[114:117]
	v_mfma_f32_16x16x32_bf16 v[86:89], v[150:153], v[174:177], v[86:89]
	v_mfma_f32_16x16x32_bf16 v[82:85], v[158:161], v[174:177], v[82:85]
	v_mfma_f32_16x16x32_bf16 v[54:57], v[150:153], v[214:217], v[54:57]
	v_mfma_f32_16x16x32_bf16 v[50:53], v[158:161], v[214:217], v[50:53]
	v_mfma_f32_16x16x32_bf16 v[22:25], v[150:153], v[232:235], v[22:25]
	v_mfma_f32_16x16x32_bf16 v[18:21], v[158:161], v[232:235], v[18:21]
	s_setprio 0
	s_barrier
	s_add_i32 s68, s68, s81
	s_mov_b32 m0, s68
	ds_read_b128 v[162:165], v187 offset:16384
	ds_read_b128 v[166:169], v187 offset:17408
	ds_read_b128 v[170:173], v187 offset:18432
	ds_read_b128 v[174:177], v187 offset:19456
	ds_read_b128 v[210:213], v187 offset:20480
	ds_read_b128 v[214:217], v187 offset:21504
	ds_read_b128 v[228:231], v187 offset:22528
	ds_read_b128 v[232:235], v187 offset:23552
	global_load_lds_dwordx4 v180, s[64:65]
	s_add_i32 m0, s68, 0x2000
	s_add_u32 s68, s64, 0x40000
	s_addc_u32 s69, s65, 0
	s_add_i32 s35, s35, s81
	global_load_lds_dwordx4 v178, s[64:65]
	s_mov_b32 m0, s35
	s_nop 0
	global_load_lds_dwordx4 v180, s[68:69]
	s_add_i32 m0, s35, 0x2000
	s_nop 0
	global_load_lds_dwordx4 v178, s[68:69]
	s_mov_b32 m0, s82
	s_nop 0
	global_load_lds_dwordx4 v180, s[66:67]
	s_mov_b32 m0, s83
	s_nop 0
	global_load_lds_dwordx4 v178, s[66:67]
	s_waitcnt vmcnt(8)
	s_waitcnt lgkmcnt(0)
	s_barrier
	s_setprio 1
	s_waitcnt lgkmcnt(0)
	v_mfma_f32_16x16x32_bf16 v[110:113], v[130:133], v[162:165], v[110:113]
	v_mfma_f32_16x16x32_bf16 v[106:109], v[138:141], v[162:165], v[106:109]
	v_mfma_f32_16x16x32_bf16 v[78:81], v[130:133], v[170:173], v[78:81]
	v_mfma_f32_16x16x32_bf16 v[74:77], v[138:141], v[170:173], v[74:77]
	v_mfma_f32_16x16x32_bf16 v[46:49], v[130:133], v[210:213], v[46:49]
	v_mfma_f32_16x16x32_bf16 v[42:45], v[138:141], v[210:213], v[42:45]
	v_mfma_f32_16x16x32_bf16 v[14:17], v[130:133], v[228:231], v[14:17]
	v_mfma_f32_16x16x32_bf16 v[10:13], v[138:141], v[228:231], v[10:13]
	v_mfma_f32_16x16x32_bf16 v[110:113], v[134:137], v[166:169], v[110:113]
	v_mfma_f32_16x16x32_bf16 v[106:109], v[142:145], v[166:169], v[106:109]
	v_mfma_f32_16x16x32_bf16 v[78:81], v[134:137], v[174:177], v[78:81]
	v_mfma_f32_16x16x32_bf16 v[74:77], v[142:145], v[174:177], v[74:77]
	v_mfma_f32_16x16x32_bf16 v[46:49], v[134:137], v[214:217], v[46:49]
	v_mfma_f32_16x16x32_bf16 v[42:45], v[142:145], v[214:217], v[42:45]
	v_mfma_f32_16x16x32_bf16 v[14:17], v[134:137], v[232:235], v[14:17]
	v_mfma_f32_16x16x32_bf16 v[10:13], v[142:145], v[232:235], v[10:13]
	s_setprio 0
	s_setprio 1
	v_mfma_f32_16x16x32_bf16 v[102:105], v[146:149], v[162:165], v[102:105]
	v_mfma_f32_16x16x32_bf16 v[98:101], v[154:157], v[162:165], v[98:101]
	v_mfma_f32_16x16x32_bf16 v[70:73], v[146:149], v[170:173], v[70:73]
	v_mfma_f32_16x16x32_bf16 v[66:69], v[154:157], v[170:173], v[66:69]
	v_mfma_f32_16x16x32_bf16 v[38:41], v[146:149], v[210:213], v[38:41]
	v_mfma_f32_16x16x32_bf16 v[34:37], v[154:157], v[210:213], v[34:37]
	v_mfma_f32_16x16x32_bf16 v[6:9], v[146:149], v[228:231], v[6:9]
	v_mfma_f32_16x16x32_bf16 v[2:5], v[154:157], v[228:231], v[2:5]
	v_mfma_f32_16x16x32_bf16 v[102:105], v[150:153], v[166:169], v[102:105]
	v_mfma_f32_16x16x32_bf16 v[98:101], v[158:161], v[166:169], v[98:101]
	v_mfma_f32_16x16x32_bf16 v[70:73], v[150:153], v[174:177], v[70:73]
	v_mfma_f32_16x16x32_bf16 v[66:69], v[158:161], v[174:177], v[66:69]
	v_mfma_f32_16x16x32_bf16 v[38:41], v[150:153], v[214:217], v[38:41]
	v_mfma_f32_16x16x32_bf16 v[34:37], v[158:161], v[214:217], v[34:37]
	v_mfma_f32_16x16x32_bf16 v[6:9], v[150:153], v[232:235], v[6:9]
	v_mfma_f32_16x16x32_bf16 v[2:5], v[158:161], v[232:235], v[2:5]
	s_setprio 0
	s_barrier
; #define PG8_STAGE(bufoff, gbase, voff) do { _Pragma("unroll") for (int _i = 0; _i < 2; ++_i) \
;         __builtin_amdgcn_global_load_lds((const unsigned*)((const char*)(gbase) + (voff)[_i]), (PG8_LAS unsigned*)(lds + (bufoff) + ldsw + _i * 8192), 16, 0, 0); } while (0)
; #define PG8_LDA(dst, b, h) do { _Pragma("unroll") for (int m = 0; m < 4; ++m) _Pragma("unroll") for (int k = 0; k < 2; ++k) dst[m][k] = *(const PG8_LAS bf16x8*)(lds + PG8_SA(b, h) + aoff + m * 2048 + k * 1024); } while (0)
; #define PG8_LDB(dst, b, h) do { _Pragma("unroll") for (int n = 0; n < 2; ++n) _Pragma("unroll") for (int k = 0; k < 2; ++k) dst[n][k] = *(const PG8_LAS bf16x8*)(lds + PG8_SB(b, h) + boff + n * 2048 + k * 1024); } while (0)
; #define PG8_MMA(ai, bj, At, Bt) do { __builtin_amdgcn_s_setprio(1); _Pragma("unroll") for (int m = 0; m < 4; ++m) _Pragma("unroll") for (int n = 0; n < 2; ++n) _Pragma("unroll") for (int k = 0; k < 2; ++k) \
;         acc[ai][bj][m][n] = __builtin_amdgcn_mfma_f32_16x16x32_bf16(Bt[n][k], At[m][k], acc[ai][bj][m][n], 0, 0, 0); __builtin_amdgcn_s_setprio(0); } while (0)
; #define PG8_WAIT_V(n) asm volatile("s_waitcnt vmcnt(" #n ")" ::: "memory")
; #define PG8_WAIT_L(n) asm volatile("s_waitcnt lgkmcnt(" #n ")" ::: "memory")
; #define PG8_BAR __builtin_amdgcn_s_barrier()
; #define PG8_SCHED __builtin_amdgcn_sched_barrier(0)
; template <class Epi, class Sched, bool ALIGN_EPI = false, bool SP2 = false>
; __device__ __forceinline__ void gemm_phase(PG8_LAS unsigned char* lds, const Gemm g, const Sched& S, const Epi& E) {
;     ...
;             PG8_LDB(B0, 1, 0); PG8_LDB(B1, 1, 1); PG8_SCHED; PG8_LDA(At, 1, 0); PG8_STAGE(PG8_SA(0, 1), a2 + hstep, voffA);
;             PG8_WAIT_V(8); PG8_WAIT_L(0); PG8_BAR; PG8_MMA(0, 0, At, B0); PG8_MMA(0, 1, At, B1); PG8_BAR; PG8_SCHED;
;             PG8_LDA(At, 1, 1); PG8_STAGE(PG8_SB(1, 0), b3, voffB); PG8_STAGE(PG8_SB(1, 1), b3 + hstep, voffB); PG8_STAGE(PG8_SA(1, 0), a3, voffA);
;             PG8_WAIT_V(8); PG8_WAIT_L(0); PG8_BAR; PG8_MMA(1, 0, At, B0); PG8_MMA(1, 1, At, B1); PG8_BAR; PG8_SCHED;
	s_add_i32 s35, 0, 0x18000
	v_add_u32_e32 v0, s35, v185
	s_add_i32 s68, 0, 0x1c000
	ds_read_b128 v[130:133], v0
	ds_read_b128 v[134:137], v0 offset:1024
	ds_read_b128 v[138:141], v0 offset:2048
	ds_read_b128 v[142:145], v0 offset:3072
	v_add_u32_e32 v0, s68, v185
	ds_read_b128 v[146:149], v0
	ds_read_b128 v[150:153], v0 offset:1024
	ds_read_b128 v[154:157], v0 offset:2048
	ds_read_b128 v[158:161], v0 offset:3072
	s_add_u32 s66, s66, 0x40000
	s_addc_u32 s67, s67, 0
	s_add_u32 s98, s66, 0xfffc0080
	s_addc_u32 s99, s67, -1
	s_mov_b32 m0, s84
	ds_read_b128 v[162:165], v187 offset:32768
	ds_read_b128 v[166:169], v187 offset:33792
	ds_read_b128 v[170:173], v187 offset:34816
	ds_read_b128 v[174:177], v187 offset:35840
	ds_read_b128 v[210:213], v187 offset:36864
	ds_read_b128 v[214:217], v187 offset:37888
	ds_read_b128 v[228:231], v187 offset:38912
	ds_read_b128 v[232:235], v187 offset:39936
	global_load_lds_dwordx4 v180, s[66:67]
	s_mov_b32 m0, s85
	s_nop 0
	global_load_lds_dwordx4 v178, s[66:67]
	s_waitcnt vmcnt(8)
	s_waitcnt lgkmcnt(0)
	s_barrier
	s_setprio 1
	s_waitcnt lgkmcnt(0)
	v_mfma_f32_16x16x32_bf16 v[126:129], v[130:133], v[162:165], v[126:129]
	v_mfma_f32_16x16x32_bf16 v[122:125], v[138:141], v[162:165], v[122:125]
	v_mfma_f32_16x16x32_bf16 v[94:97], v[130:133], v[170:173], v[94:97]
	v_mfma_f32_16x16x32_bf16 v[90:93], v[138:141], v[170:173], v[90:93]
	v_mfma_f32_16x16x32_bf16 v[62:65], v[130:133], v[210:213], v[62:65]
	v_mfma_f32_16x16x32_bf16 v[58:61], v[138:141], v[210:213], v[58:61]
	v_mfma_f32_16x16x32_bf16 v[30:33], v[130:133], v[228:231], v[30:33]
	v_mfma_f32_16x16x32_bf16 v[26:29], v[138:141], v[228:231], v[26:29]
	v_mfma_f32_16x16x32_bf16 v[126:129], v[134:137], v[166:169], v[126:129]
	v_mfma_f32_16x16x32_bf16 v[122:125], v[142:145], v[166:169], v[122:125]
	v_mfma_f32_16x16x32_bf16 v[94:97], v[134:137], v[174:177], v[94:97]
	v_mfma_f32_16x16x32_bf16 v[90:93], v[142:145], v[174:177], v[90:93]
	v_mfma_f32_16x16x32_bf16 v[62:65], v[134:137], v[214:217], v[62:65]
	v_mfma_f32_16x16x32_bf16 v[58:61], v[142:145], v[214:217], v[58:61]
	v_mfma_f32_16x16x32_bf16 v[30:33], v[134:137], v[232:235], v[30:33]
	v_mfma_f32_16x16x32_bf16 v[26:29], v[142:145], v[232:235], v[26:29]
	s_setprio 0
	s_setprio 1
	v_mfma_f32_16x16x32_bf16 v[118:121], v[146:149], v[162:165], v[118:121]
	v_mfma_f32_16x16x32_bf16 v[114:117], v[154:157], v[162:165], v[114:117]
	v_mfma_f32_16x16x32_bf16 v[86:89], v[146:149], v[170:173], v[86:89]
	v_mfma_f32_16x16x32_bf16 v[82:85], v[154:157], v[170:173], v[82:85]
	v_mfma_f32_16x16x32_bf16 v[54:57], v[146:149], v[210:213], v[54:57]
	v_mfma_f32_16x16x32_bf16 v[50:53], v[154:157], v[210:213], v[50:53]
	v_mfma_f32_16x16x32_bf16 v[22:25], v[146:149], v[228:231], v[22:25]
	v_mfma_f32_16x16x32_bf16 v[18:21], v[154:157], v[228:231], v[18:21]
	v_mfma_f32_16x16x32_bf16 v[118:121], v[150:153], v[166:169], v[118:121]
	v_mfma_f32_16x16x32_bf16 v[114:117], v[158:161], v[166:169], v[114:117]
	v_mfma_f32_16x16x32_bf16 v[86:89], v[150:153], v[174:177], v[86:89]
	v_mfma_f32_16x16x32_bf16 v[82:85], v[158:161], v[174:177], v[82:85]
	v_mfma_f32_16x16x32_bf16 v[54:57], v[150:153], v[214:217], v[54:57]
	v_mfma_f32_16x16x32_bf16 v[50:53], v[158:161], v[214:217], v[50:53]
	v_mfma_f32_16x16x32_bf16 v[22:25], v[150:153], v[232:235], v[22:25]
	v_mfma_f32_16x16x32_bf16 v[18:21], v[158:161], v[232:235], v[18:21]
	s_setprio 0
	s_barrier
	s_add_i32 s35, s35, s81
	s_add_u32 s64, s64, s38
	s_addc_u32 s65, s65, s39
	s_mov_b32 m0, s35
	ds_read_b128 v[162:165], v187 offset:49152
	ds_read_b128 v[166:169], v187 offset:50176
	ds_read_b128 v[170:173], v187 offset:51200
	ds_read_b128 v[174:177], v187 offset:52224
	ds_read_b128 v[210:213], v187 offset:53248
	ds_read_b128 v[214:217], v187 offset:54272
	ds_read_b128 v[228:231], v187 offset:55296
	ds_read_b128 v[232:235], v187 offset:56320
	global_load_lds_dwordx4 v180, s[64:65]
	s_add_i32 m0, s35, 0x2000
	s_add_i32 s35, s68, s81
	global_load_lds_dwordx4 v178, s[64:65]
	s_add_u32 s64, s64, 0x40000
	s_addc_u32 s65, s65, 0
	s_mov_b32 m0, s35
	s_nop 0
	global_load_lds_dwordx4 v180, s[64:65]
	s_add_i32 m0, s35, 0x2000
	s_nop 0
	global_load_lds_dwordx4 v178, s[64:65]
	s_mov_b32 m0, s88
	s_nop 0
	global_load_lds_dwordx4 v180, s[98:99]
	s_mov_b32 m0, s89
	s_nop 0
	global_load_lds_dwordx4 v178, s[98:99]
	s_waitcnt vmcnt(8)
	s_waitcnt lgkmcnt(0)
	s_barrier
	s_setprio 1
	s_waitcnt lgkmcnt(0)
	v_mfma_f32_16x16x32_bf16 v[110:113], v[130:133], v[162:165], v[110:113]
	v_mfma_f32_16x16x32_bf16 v[106:109], v[138:141], v[162:165], v[106:109]
	v_mfma_f32_16x16x32_bf16 v[78:81], v[130:133], v[170:173], v[78:81]
	v_mfma_f32_16x16x32_bf16 v[74:77], v[138:141], v[170:173], v[74:77]
	v_mfma_f32_16x16x32_bf16 v[46:49], v[130:133], v[210:213], v[46:49]
	v_mfma_f32_16x16x32_bf16 v[42:45], v[138:141], v[210:213], v[42:45]
	v_mfma_f32_16x16x32_bf16 v[14:17], v[130:133], v[228:231], v[14:17]
	v_mfma_f32_16x16x32_bf16 v[10:13], v[138:141], v[228:231], v[10:13]
	v_mfma_f32_16x16x32_bf16 v[110:113], v[134:137], v[166:169], v[110:113]
	v_mfma_f32_16x16x32_bf16 v[106:109], v[142:145], v[166:169], v[106:109]
	v_mfma_f32_16x16x32_bf16 v[78:81], v[134:137], v[174:177], v[78:81]
	v_mfma_f32_16x16x32_bf16 v[74:77], v[142:145], v[174:177], v[74:77]
	v_mfma_f32_16x16x32_bf16 v[46:49], v[134:137], v[214:217], v[46:49]
	v_mfma_f32_16x16x32_bf16 v[42:45], v[142:145], v[214:217], v[42:45]
	v_mfma_f32_16x16x32_bf16 v[14:17], v[134:137], v[232:235], v[14:17]
	v_mfma_f32_16x16x32_bf16 v[10:13], v[142:145], v[232:235], v[10:13]
	s_setprio 0
	s_setprio 1
	v_mfma_f32_16x16x32_bf16 v[102:105], v[146:149], v[162:165], v[102:105]
	v_mfma_f32_16x16x32_bf16 v[98:101], v[154:157], v[162:165], v[98:101]
	v_mfma_f32_16x16x32_bf16 v[70:73], v[146:149], v[170:173], v[70:73]
	v_mfma_f32_16x16x32_bf16 v[66:69], v[154:157], v[170:173], v[66:69]
	v_mfma_f32_16x16x32_bf16 v[38:41], v[146:149], v[210:213], v[38:41]
	v_mfma_f32_16x16x32_bf16 v[34:37], v[154:157], v[210:213], v[34:37]
	v_mfma_f32_16x16x32_bf16 v[6:9], v[146:149], v[228:231], v[6:9]
	v_mfma_f32_16x16x32_bf16 v[2:5], v[154:157], v[228:231], v[2:5]
	v_mfma_f32_16x16x32_bf16 v[102:105], v[150:153], v[166:169], v[102:105]
	v_mfma_f32_16x16x32_bf16 v[98:101], v[158:161], v[166:169], v[98:101]
	v_mfma_f32_16x16x32_bf16 v[70:73], v[150:153], v[174:177], v[70:73]
	v_mfma_f32_16x16x32_bf16 v[66:69], v[158:161], v[174:177], v[66:69]
	v_mfma_f32_16x16x32_bf16 v[38:41], v[150:153], v[214:217], v[38:41]
	v_mfma_f32_16x16x32_bf16 v[34:37], v[158:161], v[214:217], v[34:37]
	v_mfma_f32_16x16x32_bf16 v[6:9], v[150:153], v[232:235], v[6:9]
	v_mfma_f32_16x16x32_bf16 v[2:5], v[158:161], v[232:235], v[2:5]
	s_setprio 0
	s_barrier
	s_add_i32 s33, s33, 2
	s_add_u32 s28, s28, 0x100
	s_addc_u32 s29, s29, 0
	s_add_u32 s62, s62, 0x100
	s_addc_u32 s63, s63, 0
	s_cmp_gt_u32 s33, 13
	s_cbranch_scc0 .LBB0_230
	s_and_b64 vcc, exec, s[48:49]
	s_cbranch_vccz .LBB0_233
	s_barrier

; #define PG8_STAGE(bufoff, gbase, voff) do { _Pragma("unroll") for (int _i = 0; _i < 2; ++_i) \
;         __builtin_amdgcn_global_load_lds((const unsigned*)((const char*)(gbase) + (voff)[_i]), (PG8_LAS unsigned*)(lds + (bufoff) + ldsw + _i * 8192), 16, 0, 0); } while (0)
; #define PG8_LDA(dst, b, h) do { _Pragma("unroll") for (int m = 0; m < 4; ++m) _Pragma("unroll") for (int k = 0; k < 2; ++k) dst[m][k] = *(const PG8_LAS bf16x8*)(lds + PG8_SA(b, h) + aoff + m * 2048 + k * 1024); } while (0)
; #define PG8_LDB(dst, b, h) do { _Pragma("unroll") for (int n = 0; n < 2; ++n) _Pragma("unroll") for (int k = 0; k < 2; ++k) dst[n][k] = *(const PG8_LAS bf16x8*)(lds + PG8_SB(b, h) + boff + n * 2048 + k * 1024); } while (0)
; #define PG8_MMA(ai, bj, At, Bt) do { __builtin_amdgcn_s_setprio(1); _Pragma("unroll") for (int m = 0; m < 4; ++m) _Pragma("unroll") for (int n = 0; n < 2; ++n) _Pragma("unroll") for (int k = 0; k < 2; ++k) \
;         acc[ai][bj][m][n] = __builtin_amdgcn_mfma_f32_16x16x32_bf16(Bt[n][k], At[m][k], acc[ai][bj][m][n], 0, 0, 0); __builtin_amdgcn_s_setprio(0); } while (0)
; #define PG8_WAIT_V(n) asm volatile("s_waitcnt vmcnt(" #n ")" ::: "memory")
; #define PG8_WAIT_L(n) asm volatile("s_waitcnt lgkmcnt(" #n ")" ::: "memory")
; #define PG8_BAR __builtin_amdgcn_s_barrier()
; #define PG8_SCHED __builtin_amdgcn_sched_barrier(0)
; template <class Epi, class Sched, bool ALIGN_EPI = false, bool SP2 = false>
; __device__ __forceinline__ void gemm_phase(PG8_LAS unsigned char* lds, const Gemm g, const Sched& S, const Epi& E) {
;     ...
;             PG8_LDB(B0, 0, 0); PG8_LDB(B1, 0, 1); PG8_SCHED; PG8_LDA(At, 0, 0); PG8_STAGE(PG8_SA(1, 1), a1 + hstep, voffA);
;             PG8_WAIT_V(8); PG8_WAIT_L(0); PG8_BAR; PG8_MMA(0, 0, At, B0); PG8_MMA(0, 1, At, B1); PG8_BAR; PG8_SCHED;
;             PG8_LDA(At, 0, 1); PG8_STAGE(PG8_SB(0, 0), b2, voffB); PG8_STAGE(PG8_SB(0, 1), b2 + hstep, voffB); PG8_STAGE(PG8_SA(0, 0), a2, voffA);
;             PG8_WAIT_V(8); PG8_WAIT_L(0); PG8_BAR; PG8_MMA(1, 0, At, B0); PG8_MMA(1, 1, At, B1); PG8_BAR; PG8_SCHED;
.LBB0_678:
	s_add_u32 s60, s42, 0xfffc0080
	s_addc_u32 s61, s43, -1
	s_add_i32 s80, 0, 0x10000
	s_cmp_eq_u32 s79, 12
	s_cselect_b32 s63, s49, s61
	s_cselect_b32 s62, s75, s60
	v_add_u32_e32 v0, s80, v159
	s_cselect_b32 s61, s47, s78
	s_cselect_b32 s60, s76, s77
	s_add_i32 s82, 0, 0x14000
	ds_read_b128 v[102:105], v0
	ds_read_b128 v[110:113], v0 offset:1024
	ds_read_b128 v[114:117], v0 offset:2048
	ds_read_b128 v[118:121], v0 offset:3072
	v_add_u32_e32 v0, s82, v159
	ds_read_b128 v[162:165], v0
	ds_read_b128 v[166:169], v0 offset:1024
	ds_read_b128 v[170:173], v0 offset:2048
	ds_read_b128 v[174:177], v0 offset:3072
	s_add_i32 m0, s28, 0xc000
	ds_read_b128 v[178:181], v161
	ds_read_b128 v[182:185], v161 offset:1024
	ds_read_b128 v[186:189], v161 offset:2048
	ds_read_b128 v[202:205], v161 offset:3072
	ds_read_b128 v[206:209], v161 offset:4096
	ds_read_b128 v[210:213], v161 offset:5120
	ds_read_b128 v[214:217], v161 offset:6144
	ds_read_b128 v[228:231], v161 offset:7168
	global_load_lds_dwordx4 v156, s[42:43]
	s_add_i32 m0, s28, 0xe000
	s_nop 0
	global_load_lds_dwordx4 v154, s[42:43]
	s_waitcnt vmcnt(8)
	s_waitcnt lgkmcnt(0)
	s_barrier
	s_setprio 1
	s_waitcnt lgkmcnt(0)
	v_mfma_f32_16x16x32_bf16 v[142:145], v[102:105], v[178:181], v[142:145]
	v_mfma_f32_16x16x32_bf16 v[138:141], v[114:117], v[178:181], v[138:141]
	v_mfma_f32_16x16x32_bf16 v[126:129], v[102:105], v[186:189], v[126:129]
	v_mfma_f32_16x16x32_bf16 v[122:125], v[114:117], v[186:189], v[122:125]
	v_mfma_f32_16x16x32_bf16 v[94:97], v[102:105], v[206:209], v[94:97]
	v_mfma_f32_16x16x32_bf16 v[90:93], v[114:117], v[206:209], v[90:93]
	v_mfma_f32_16x16x32_bf16 v[82:85], v[102:105], v[214:217], v[82:85]
	v_mfma_f32_16x16x32_bf16 v[74:77], v[114:117], v[214:217], v[74:77]
	v_mfma_f32_16x16x32_bf16 v[142:145], v[110:113], v[182:185], v[142:145]
	v_mfma_f32_16x16x32_bf16 v[138:141], v[118:121], v[182:185], v[138:141]
	v_mfma_f32_16x16x32_bf16 v[126:129], v[110:113], v[202:205], v[126:129]
	v_mfma_f32_16x16x32_bf16 v[122:125], v[118:121], v[202:205], v[122:125]
	v_mfma_f32_16x16x32_bf16 v[94:97], v[110:113], v[210:213], v[94:97]
	v_mfma_f32_16x16x32_bf16 v[90:93], v[118:121], v[210:213], v[90:93]
	v_mfma_f32_16x16x32_bf16 v[82:85], v[110:113], v[228:231], v[82:85]
	v_mfma_f32_16x16x32_bf16 v[74:77], v[118:121], v[228:231], v[74:77]
	s_setprio 0
	s_setprio 1
	v_mfma_f32_16x16x32_bf16 v[134:137], v[162:165], v[178:181], v[134:137]
	v_mfma_f32_16x16x32_bf16 v[130:133], v[170:173], v[178:181], v[130:133]
	v_mfma_f32_16x16x32_bf16 v[106:109], v[162:165], v[186:189], v[106:109]
	v_mfma_f32_16x16x32_bf16 v[98:101], v[170:173], v[186:189], v[98:101]
	v_mfma_f32_16x16x32_bf16 v[86:89], v[162:165], v[206:209], v[86:89]
	v_mfma_f32_16x16x32_bf16 v[78:81], v[170:173], v[206:209], v[78:81]
	v_mfma_f32_16x16x32_bf16 v[70:73], v[162:165], v[214:217], v[70:73]
	v_mfma_f32_16x16x32_bf16 v[66:69], v[170:173], v[214:217], v[66:69]
	v_mfma_f32_16x16x32_bf16 v[134:137], v[166:169], v[182:185], v[134:137]
	v_mfma_f32_16x16x32_bf16 v[130:133], v[174:177], v[182:185], v[130:133]
	v_mfma_f32_16x16x32_bf16 v[106:109], v[166:169], v[202:205], v[106:109]
	v_mfma_f32_16x16x32_bf16 v[98:101], v[174:177], v[202:205], v[98:101]
	v_mfma_f32_16x16x32_bf16 v[86:89], v[166:169], v[210:213], v[86:89]
	v_mfma_f32_16x16x32_bf16 v[78:81], v[174:177], v[210:213], v[78:81]
	v_mfma_f32_16x16x32_bf16 v[70:73], v[166:169], v[228:231], v[70:73]
	v_mfma_f32_16x16x32_bf16 v[66:69], v[174:177], v[228:231], v[66:69]
	s_setprio 0
	s_barrier
	s_add_i32 s80, s80, s20
	s_mov_b32 m0, s80
	ds_read_b128 v[178:181], v161 offset:16384
	ds_read_b128 v[182:185], v161 offset:17408
	ds_read_b128 v[186:189], v161 offset:18432
	ds_read_b128 v[202:205], v161 offset:19456
	ds_read_b128 v[206:209], v161 offset:20480
	ds_read_b128 v[210:213], v161 offset:21504
	ds_read_b128 v[214:217], v161 offset:22528
	ds_read_b128 v[228:231], v161 offset:23552
	global_load_lds_dwordx4 v150, s[60:61]
	s_add_i32 m0, s80, 0x2000
	s_add_u32 s80, s60, 0x40000
	s_addc_u32 s81, s61, 0
	s_add_i32 s82, s82, s20
	global_load_lds_dwordx4 v146, s[60:61]
	s_mov_b32 m0, s82
	s_nop 0
	global_load_lds_dwordx4 v150, s[80:81]
	s_add_i32 m0, s82, 0x2000
	s_nop 0
	global_load_lds_dwordx4 v146, s[80:81]
	s_mov_b32 m0, s28
	s_nop 0
	global_load_lds_dwordx4 v152, s[62:63]
	s_mov_b32 m0, s29
	s_nop 0
	global_load_lds_dwordx4 v148, s[62:63]
	s_waitcnt vmcnt(8)
	s_waitcnt lgkmcnt(0)
	s_barrier
	s_setprio 1
	s_waitcnt lgkmcnt(0)
	v_mfma_f32_16x16x32_bf16 v[62:65], v[102:105], v[178:181], v[62:65]
	v_mfma_f32_16x16x32_bf16 v[58:61], v[114:117], v[178:181], v[58:61]
	v_mfma_f32_16x16x32_bf16 v[50:53], v[102:105], v[186:189], v[50:53]
	v_mfma_f32_16x16x32_bf16 v[42:45], v[114:117], v[186:189], v[42:45]
	v_mfma_f32_16x16x32_bf16 v[34:37], v[102:105], v[206:209], v[34:37]
	v_mfma_f32_16x16x32_bf16 v[26:29], v[114:117], v[206:209], v[26:29]
	v_mfma_f32_16x16x32_bf16 v[18:21], v[102:105], v[214:217], v[18:21]
	v_mfma_f32_16x16x32_bf16 v[10:13], v[114:117], v[214:217], v[10:13]
	v_mfma_f32_16x16x32_bf16 v[62:65], v[110:113], v[182:185], v[62:65]
	v_mfma_f32_16x16x32_bf16 v[58:61], v[118:121], v[182:185], v[58:61]
	v_mfma_f32_16x16x32_bf16 v[50:53], v[110:113], v[202:205], v[50:53]
	v_mfma_f32_16x16x32_bf16 v[42:45], v[118:121], v[202:205], v[42:45]
	v_mfma_f32_16x16x32_bf16 v[34:37], v[110:113], v[210:213], v[34:37]
	v_mfma_f32_16x16x32_bf16 v[26:29], v[118:121], v[210:213], v[26:29]
	v_mfma_f32_16x16x32_bf16 v[18:21], v[110:113], v[228:231], v[18:21]
	v_mfma_f32_16x16x32_bf16 v[10:13], v[118:121], v[228:231], v[10:13]
	s_setprio 0
	s_setprio 1
	v_mfma_f32_16x16x32_bf16 v[54:57], v[162:165], v[178:181], v[54:57]
	v_mfma_f32_16x16x32_bf16 v[46:49], v[170:173], v[178:181], v[46:49]
	v_mfma_f32_16x16x32_bf16 v[38:41], v[162:165], v[186:189], v[38:41]
	v_mfma_f32_16x16x32_bf16 v[30:33], v[170:173], v[186:189], v[30:33]
	v_mfma_f32_16x16x32_bf16 v[22:25], v[162:165], v[206:209], v[22:25]
	v_mfma_f32_16x16x32_bf16 v[14:17], v[170:173], v[206:209], v[14:17]
	v_mfma_f32_16x16x32_bf16 v[6:9], v[162:165], v[214:217], v[6:9]
	v_mfma_f32_16x16x32_bf16 v[2:5], v[170:173], v[214:217], v[2:5]
	v_mfma_f32_16x16x32_bf16 v[54:57], v[166:169], v[182:185], v[54:57]
	v_mfma_f32_16x16x32_bf16 v[46:49], v[174:177], v[182:185], v[46:49]
	v_mfma_f32_16x16x32_bf16 v[38:41], v[166:169], v[202:205], v[38:41]
	v_mfma_f32_16x16x32_bf16 v[30:33], v[174:177], v[202:205], v[30:33]
	v_mfma_f32_16x16x32_bf16 v[22:25], v[166:169], v[210:213], v[22:25]
	v_mfma_f32_16x16x32_bf16 v[14:17], v[174:177], v[210:213], v[14:17]
	v_mfma_f32_16x16x32_bf16 v[6:9], v[166:169], v[228:231], v[6:9]
	v_mfma_f32_16x16x32_bf16 v[2:5], v[174:177], v[228:231], v[2:5]
	s_setprio 0
	s_barrier
; #define PG8_STAGE(bufoff, gbase, voff) do { _Pragma("unroll") for (int _i = 0; _i < 2; ++_i) \
;         __builtin_amdgcn_global_load_lds((const unsigned*)((const char*)(gbase) + (voff)[_i]), (PG8_LAS unsigned*)(lds + (bufoff) + ldsw + _i * 8192), 16, 0, 0); } while (0)
; #define PG8_LDA(dst, b, h) do { _Pragma("unroll") for (int m = 0; m < 4; ++m) _Pragma("unroll") for (int k = 0; k < 2; ++k) dst[m][k] = *(const PG8_LAS bf16x8*)(lds + PG8_SA(b, h) + aoff + m * 2048 + k * 1024); } while (0)
; #define PG8_LDB(dst, b, h) do { _Pragma("unroll") for (int n = 0; n < 2; ++n) _Pragma("unroll") for (int k = 0; k < 2; ++k) dst[n][k] = *(const PG8_LAS bf16x8*)(lds + PG8_SB(b, h) + boff + n * 2048 + k * 1024); } while (0)
; #define PG8_MMA(ai, bj, At, Bt) do { __builtin_amdgcn_s_setprio(1); _Pragma("unroll") for (int m = 0; m < 4; ++m) _Pragma("unroll") for (int n = 0; n < 2; ++n) _Pragma("unroll") for (int k = 0; k < 2; ++k) \
;         acc[ai][bj][m][n] = __builtin_amdgcn_mfma_f32_16x16x32_bf16(Bt[n][k], At[m][k], acc[ai][bj][m][n], 0, 0, 0); __builtin_amdgcn_s_setprio(0); } while (0)
; #define PG8_WAIT_V(n) asm volatile("s_waitcnt vmcnt(" #n ")" ::: "memory")
; #define PG8_WAIT_L(n) asm volatile("s_waitcnt lgkmcnt(" #n ")" ::: "memory")
; #define PG8_BAR __builtin_amdgcn_s_barrier()
; #define PG8_SCHED __builtin_amdgcn_sched_barrier(0)
; template <class Epi, class Sched, bool ALIGN_EPI = false, bool SP2 = false>
; __device__ __forceinline__ void gemm_phase(PG8_LAS unsigned char* lds, const Gemm g, const Sched& S, const Epi& E) {
;     ...
;         for (int t = 0; t < nt; t += 2) {
;     ...
;             PG8_LDB(B0, 1, 0); PG8_LDB(B1, 1, 1); PG8_SCHED; PG8_LDA(At, 1, 0); PG8_STAGE(PG8_SA(0, 1), a2 + hstep, voffA);
;             PG8_WAIT_V(8); PG8_WAIT_L(0); PG8_BAR; PG8_MMA(0, 0, At, B0); PG8_MMA(0, 1, At, B1); PG8_BAR; PG8_SCHED;
;             PG8_LDA(At, 1, 1); PG8_STAGE(PG8_SB(1, 0), b3, voffB); PG8_STAGE(PG8_SB(1, 1), b3 + hstep, voffB); PG8_STAGE(PG8_SA(1, 0), a3, voffA);
;             PG8_WAIT_V(8); PG8_WAIT_L(0); PG8_BAR; PG8_MMA(1, 0, At, B0); PG8_MMA(1, 1, At, B1); PG8_BAR; PG8_SCHED;
	s_add_i32 s80, 0, 0x18000
	v_add_u32_e32 v0, s80, v159
	s_add_i32 s81, 0, 0x1c000
	ds_read_b128 v[102:105], v0
	ds_read_b128 v[110:113], v0 offset:1024
	ds_read_b128 v[114:117], v0 offset:2048
	ds_read_b128 v[118:121], v0 offset:3072
	v_add_u32_e32 v0, s81, v159
	ds_read_b128 v[162:165], v0
	ds_read_b128 v[166:169], v0 offset:1024
	ds_read_b128 v[170:173], v0 offset:2048
	ds_read_b128 v[174:177], v0 offset:3072
	s_add_u32 s62, s62, 0x40000
	s_addc_u32 s63, s63, 0
	s_add_u32 s98, s62, 0xfffc0080
	s_addc_u32 s99, s63, -1
	s_mov_b32 m0, s33
	ds_read_b128 v[178:181], v161 offset:32768
	ds_read_b128 v[182:185], v161 offset:33792
	ds_read_b128 v[186:189], v161 offset:34816
	ds_read_b128 v[202:205], v161 offset:35840
	ds_read_b128 v[206:209], v161 offset:36864
	ds_read_b128 v[210:213], v161 offset:37888
	ds_read_b128 v[214:217], v161 offset:38912
	ds_read_b128 v[228:231], v161 offset:39936
	global_load_lds_dwordx4 v152, s[62:63]
	s_mov_b32 m0, s64
	s_nop 0
	global_load_lds_dwordx4 v148, s[62:63]
	s_waitcnt vmcnt(8)
	s_waitcnt lgkmcnt(0)
	s_barrier
	s_setprio 1
	s_waitcnt lgkmcnt(0)
	v_mfma_f32_16x16x32_bf16 v[142:145], v[102:105], v[178:181], v[142:145]
	v_mfma_f32_16x16x32_bf16 v[138:141], v[114:117], v[178:181], v[138:141]
	v_mfma_f32_16x16x32_bf16 v[126:129], v[102:105], v[186:189], v[126:129]
	v_mfma_f32_16x16x32_bf16 v[122:125], v[114:117], v[186:189], v[122:125]
	v_mfma_f32_16x16x32_bf16 v[94:97], v[102:105], v[206:209], v[94:97]
	v_mfma_f32_16x16x32_bf16 v[90:93], v[114:117], v[206:209], v[90:93]
	v_mfma_f32_16x16x32_bf16 v[82:85], v[102:105], v[214:217], v[82:85]
	v_mfma_f32_16x16x32_bf16 v[74:77], v[114:117], v[214:217], v[74:77]
	v_mfma_f32_16x16x32_bf16 v[142:145], v[110:113], v[182:185], v[142:145]
	v_mfma_f32_16x16x32_bf16 v[138:141], v[118:121], v[182:185], v[138:141]
	v_mfma_f32_16x16x32_bf16 v[126:129], v[110:113], v[202:205], v[126:129]
	v_mfma_f32_16x16x32_bf16 v[122:125], v[118:121], v[202:205], v[122:125]
	v_mfma_f32_16x16x32_bf16 v[94:97], v[110:113], v[210:213], v[94:97]
	v_mfma_f32_16x16x32_bf16 v[90:93], v[118:121], v[210:213], v[90:93]
	v_mfma_f32_16x16x32_bf16 v[82:85], v[110:113], v[228:231], v[82:85]
	v_mfma_f32_16x16x32_bf16 v[74:77], v[118:121], v[228:231], v[74:77]
	s_setprio 0
	s_setprio 1
	v_mfma_f32_16x16x32_bf16 v[134:137], v[162:165], v[178:181], v[134:137]
	v_mfma_f32_16x16x32_bf16 v[130:133], v[170:173], v[178:181], v[130:133]
	v_mfma_f32_16x16x32_bf16 v[106:109], v[162:165], v[186:189], v[106:109]
	v_mfma_f32_16x16x32_bf16 v[98:101], v[170:173], v[186:189], v[98:101]
	v_mfma_f32_16x16x32_bf16 v[86:89], v[162:165], v[206:209], v[86:89]
	v_mfma_f32_16x16x32_bf16 v[78:81], v[170:173], v[206:209], v[78:81]
	v_mfma_f32_16x16x32_bf16 v[70:73], v[162:165], v[214:217], v[70:73]
	v_mfma_f32_16x16x32_bf16 v[66:69], v[170:173], v[214:217], v[66:69]
	v_mfma_f32_16x16x32_bf16 v[134:137], v[166:169], v[182:185], v[134:137]
	v_mfma_f32_16x16x32_bf16 v[130:133], v[174:177], v[182:185], v[130:133]
	v_mfma_f32_16x16x32_bf16 v[106:109], v[166:169], v[202:205], v[106:109]
	v_mfma_f32_16x16x32_bf16 v[98:101], v[174:177], v[202:205], v[98:101]
	v_mfma_f32_16x16x32_bf16 v[86:89], v[166:169], v[210:213], v[86:89]
	v_mfma_f32_16x16x32_bf16 v[78:81], v[174:177], v[210:213], v[78:81]
	v_mfma_f32_16x16x32_bf16 v[70:73], v[166:169], v[228:231], v[70:73]
	v_mfma_f32_16x16x32_bf16 v[66:69], v[174:177], v[228:231], v[66:69]
	s_setprio 0
	s_barrier
	s_add_i32 s62, s80, s20
	s_add_u32 s60, s60, s38
	s_addc_u32 s61, s61, s39
	s_mov_b32 m0, s62
	ds_read_b128 v[178:181], v161 offset:49152
	ds_read_b128 v[182:185], v161 offset:50176
	ds_read_b128 v[186:189], v161 offset:51200
	ds_read_b128 v[202:205], v161 offset:52224
	ds_read_b128 v[206:209], v161 offset:53248
	ds_read_b128 v[210:213], v161 offset:54272
	ds_read_b128 v[214:217], v161 offset:55296
	ds_read_b128 v[228:231], v161 offset:56320
	global_load_lds_dwordx4 v150, s[60:61]
	s_add_i32 m0, s62, 0x2000
	s_add_i32 s62, s81, s20
	global_load_lds_dwordx4 v146, s[60:61]
	s_add_u32 s60, s60, 0x40000
	s_addc_u32 s61, s61, 0
	s_mov_b32 m0, s62
	s_nop 0
	global_load_lds_dwordx4 v150, s[60:61]
	s_add_i32 m0, s62, 0x2000
	s_nop 0
	global_load_lds_dwordx4 v146, s[60:61]
	s_mov_b32 m0, s69
	s_nop 0
	global_load_lds_dwordx4 v152, s[98:99]
	s_mov_b32 m0, s70
	s_nop 0
	global_load_lds_dwordx4 v148, s[98:99]
	s_waitcnt vmcnt(8)
	s_waitcnt lgkmcnt(0)
	s_barrier
	s_setprio 1
	s_waitcnt lgkmcnt(0)
	v_mfma_f32_16x16x32_bf16 v[62:65], v[102:105], v[178:181], v[62:65]
	v_mfma_f32_16x16x32_bf16 v[58:61], v[114:117], v[178:181], v[58:61]
	v_mfma_f32_16x16x32_bf16 v[50:53], v[102:105], v[186:189], v[50:53]
	v_mfma_f32_16x16x32_bf16 v[42:45], v[114:117], v[186:189], v[42:45]
	v_mfma_f32_16x16x32_bf16 v[34:37], v[102:105], v[206:209], v[34:37]
	v_mfma_f32_16x16x32_bf16 v[26:29], v[114:117], v[206:209], v[26:29]
	v_mfma_f32_16x16x32_bf16 v[18:21], v[102:105], v[214:217], v[18:21]
	v_mfma_f32_16x16x32_bf16 v[10:13], v[114:117], v[214:217], v[10:13]
	v_mfma_f32_16x16x32_bf16 v[62:65], v[110:113], v[182:185], v[62:65]
	v_mfma_f32_16x16x32_bf16 v[58:61], v[118:121], v[182:185], v[58:61]
	v_mfma_f32_16x16x32_bf16 v[50:53], v[110:113], v[202:205], v[50:53]
	v_mfma_f32_16x16x32_bf16 v[42:45], v[118:121], v[202:205], v[42:45]
	v_mfma_f32_16x16x32_bf16 v[34:37], v[110:113], v[210:213], v[34:37]
	v_mfma_f32_16x16x32_bf16 v[26:29], v[118:121], v[210:213], v[26:29]
	v_mfma_f32_16x16x32_bf16 v[18:21], v[110:113], v[228:231], v[18:21]
	v_mfma_f32_16x16x32_bf16 v[10:13], v[118:121], v[228:231], v[10:13]
	s_setprio 0
	s_setprio 1
	v_mfma_f32_16x16x32_bf16 v[54:57], v[162:165], v[178:181], v[54:57]
	v_mfma_f32_16x16x32_bf16 v[46:49], v[170:173], v[178:181], v[46:49]
	v_mfma_f32_16x16x32_bf16 v[38:41], v[162:165], v[186:189], v[38:41]
	v_mfma_f32_16x16x32_bf16 v[30:33], v[170:173], v[186:189], v[30:33]
	v_mfma_f32_16x16x32_bf16 v[22:25], v[162:165], v[206:209], v[22:25]
	v_mfma_f32_16x16x32_bf16 v[14:17], v[170:173], v[206:209], v[14:17]
	v_mfma_f32_16x16x32_bf16 v[6:9], v[162:165], v[214:217], v[6:9]
	v_mfma_f32_16x16x32_bf16 v[2:5], v[170:173], v[214:217], v[2:5]
	v_mfma_f32_16x16x32_bf16 v[54:57], v[166:169], v[182:185], v[54:57]
	v_mfma_f32_16x16x32_bf16 v[46:49], v[174:177], v[182:185], v[46:49]
	v_mfma_f32_16x16x32_bf16 v[38:41], v[166:169], v[202:205], v[38:41]
	v_mfma_f32_16x16x32_bf16 v[30:33], v[174:177], v[202:205], v[30:33]
	v_mfma_f32_16x16x32_bf16 v[22:25], v[166:169], v[210:213], v[22:25]
	v_mfma_f32_16x16x32_bf16 v[14:17], v[174:177], v[210:213], v[14:17]
	v_mfma_f32_16x16x32_bf16 v[6:9], v[166:169], v[228:231], v[6:9]
	v_mfma_f32_16x16x32_bf16 v[2:5], v[174:177], v[228:231], v[2:5]
	s_setprio 0
	s_barrier
	s_add_i32 s79, s79, 2
	s_add_u32 s77, s77, 0x100
	s_addc_u32 s78, s78, 0
	s_add_u32 s42, s42, 0x100
	s_addc_u32 s43, s43, 0
	s_cmp_gt_u32 s79, 13
	s_cbranch_scc0 .LBB0_678
	s_and_b64 vcc, exec, s[44:45]
	s_movk_i32 s75, 0x1000
	s_cbranch_vccz .LBB0_681
	s_barrier
